# baseline (speedup 1.0000x reference)
.Lh2_loop:
	ds_read_b128 v[140:143], v138
	ds_read_b128 v[144:147], v138 offset:1024
	ds_read_b128 v[148:151], v138 offset:2048
	ds_read_b128 v[152:155], v138 offset:3072
	s_add_u32 s8, s6, s65
	v_mov_b32_e32 v196, v129
	v_mov_b32_e32 v188, v130
	s_addc_u32 s9, s7, s66
	ds_read_b128 v[156:159], v134
	ds_read_b128 v[160:163], v134 offset:1024
	ds_read_b128 v[164:167], v133
	ds_read_b128 v[168:171], v133 offset:1024
	ds_read_b128 v[172:175], v132
	ds_read_b128 v[176:179], v132 offset:1024
	ds_read_b128 v[180:183], v131
	ds_read_b128 v[184:187], v131 offset:1024
	v_mov_b32_e32 v189, v197
	v_lshl_add_u64 v[190:191], s[8:9], 0, v[196:197]
	s_mov_b32 m0, s76
	v_lshl_add_u64 v[190:191], v[190:191], 0, s[44:45]
	v_lshl_add_u64 v[188:189], s[8:9], 0, v[188:189]
	v_lshl_add_u64 v[188:189], v[188:189], 0, s[44:45]
	s_mov_b32 m0, s75
	s_nop 0
	s_waitcnt lgkmcnt(8)
	s_barrier
	s_waitcnt lgkmcnt(0)
	s_setprio 1
	s_waitcnt lgkmcnt(0)
	v_mfma_f32_16x16x32_bf16 v[124:127], v[140:143], v[156:159], v[124:127]
	v_mfma_f32_16x16x32_bf16 v[120:123], v[148:151], v[156:159], v[120:123]
	v_mfma_f32_16x16x32_bf16 v[116:119], v[140:143], v[164:167], v[116:119]
	v_mfma_f32_16x16x32_bf16 v[112:115], v[148:151], v[164:167], v[112:115]
	v_mfma_f32_16x16x32_bf16 v[108:111], v[140:143], v[172:175], v[108:111]
	v_mfma_f32_16x16x32_bf16 v[104:107], v[148:151], v[172:175], v[104:107]
	v_mfma_f32_16x16x32_bf16 v[100:103], v[140:143], v[180:183], v[100:103]
	v_mfma_f32_16x16x32_bf16 v[96:99], v[148:151], v[180:183], v[96:99]
	v_mfma_f32_16x16x32_bf16 v[124:127], v[144:147], v[160:163], v[124:127]
	v_mfma_f32_16x16x32_bf16 v[120:123], v[152:155], v[160:163], v[120:123]
	v_mfma_f32_16x16x32_bf16 v[116:119], v[144:147], v[168:171], v[116:119]
	v_mfma_f32_16x16x32_bf16 v[112:115], v[152:155], v[168:171], v[112:115]
	v_mfma_f32_16x16x32_bf16 v[108:111], v[144:147], v[176:179], v[108:111]
	v_mfma_f32_16x16x32_bf16 v[104:107], v[152:155], v[176:179], v[104:107]
	v_mfma_f32_16x16x32_bf16 v[100:103], v[144:147], v[184:187], v[100:103]
	v_mfma_f32_16x16x32_bf16 v[96:99], v[152:155], v[184:187], v[96:99]
	s_setprio 0
	s_barrier
	s_add_u32 s10, s6, s36
	v_mov_b32_e32 v196, v129
	v_mov_b32_e32 v210, v130
	s_addc_u32 s11, s7, s37
	ds_read_b128 v[188:191], v137
	ds_read_b128 v[192:195], v137 offset:1024
	ds_read_b128 v[202:205], v137 offset:2048
	ds_read_b128 v[206:209], v137 offset:3072
	v_mov_b32_e32 v211, v197
	v_lshl_add_u64 v[212:213], s[10:11], 0, v[196:197]
	s_mov_b32 m0, s63
	v_lshl_add_u64 v[212:213], v[212:213], 0, s[46:47]
	v_lshl_add_u64 v[210:211], s[10:11], 0, v[210:211]
	global_load_lds_dwordx4 v[212:213], off
	v_lshl_add_u64 v[210:211], v[210:211], 0, s[46:47]
	s_mov_b32 m0, s64
	s_nop 0
	global_load_lds_dwordx4 v[210:211], off
	s_barrier
	s_waitcnt lgkmcnt(0)
	s_setprio 1
	s_waitcnt lgkmcnt(0)
	v_mfma_f32_16x16x32_bf16 v[92:95], v[188:191], v[156:159], v[92:95]
	v_mfma_f32_16x16x32_bf16 v[88:91], v[202:205], v[156:159], v[88:91]
	v_mfma_f32_16x16x32_bf16 v[84:87], v[188:191], v[164:167], v[84:87]
	v_mfma_f32_16x16x32_bf16 v[80:83], v[202:205], v[164:167], v[80:83]
	v_mfma_f32_16x16x32_bf16 v[76:79], v[188:191], v[172:175], v[76:79]
	v_mfma_f32_16x16x32_bf16 v[72:75], v[202:205], v[172:175], v[72:75]
	v_mfma_f32_16x16x32_bf16 v[68:71], v[188:191], v[180:183], v[68:71]
	v_mfma_f32_16x16x32_bf16 v[64:67], v[202:205], v[180:183], v[64:67]
	v_mfma_f32_16x16x32_bf16 v[92:95], v[192:195], v[160:163], v[92:95]
	v_mfma_f32_16x16x32_bf16 v[88:91], v[206:209], v[160:163], v[88:91]
	v_mfma_f32_16x16x32_bf16 v[84:87], v[192:195], v[168:171], v[84:87]
	v_mfma_f32_16x16x32_bf16 v[80:83], v[206:209], v[168:171], v[80:83]
	v_mfma_f32_16x16x32_bf16 v[76:79], v[192:195], v[176:179], v[76:79]
	v_mfma_f32_16x16x32_bf16 v[72:75], v[206:209], v[176:179], v[72:75]
	v_mfma_f32_16x16x32_bf16 v[68:71], v[192:195], v[184:187], v[68:71]
	v_mfma_f32_16x16x32_bf16 v[64:67], v[206:209], v[184:187], v[64:67]
	s_setprio 0
	v_mov_b32_e32 v196, v129
	v_mov_b32_e32 v210, v130
	s_barrier
	v_mov_b32_e32 v211, v197
	v_lshl_add_u64 v[212:213], s[8:9], 0, v[196:197]
	s_mov_b32 m0, s62
	v_lshl_add_u64 v[212:213], v[212:213], 0, s[48:49]
	v_lshl_add_u64 v[210:211], s[8:9], 0, v[210:211]
	global_load_lds_dwordx4 v[212:213], off
	v_lshl_add_u64 v[210:211], v[210:211], 0, s[48:49]
	s_mov_b32 m0, s67
	s_nop 0
	global_load_lds_dwordx4 v[210:211], off
	s_waitcnt vmcnt(4)
	s_barrier
	v_mov_b32_e32 v196, v129
	v_mov_b32_e32 v140, v130
	v_mov_b32_e32 v141, v197
	v_lshl_add_u64 v[142:143], s[10:11], 0, v[196:197]
	s_mov_b32 m0, s68
	v_lshl_add_u64 v[142:143], v[142:143], 0, s[50:51]
	v_lshl_add_u64 v[140:141], s[10:11], 0, v[140:141]
	global_load_lds_dwordx4 v[142:143], off
	v_lshl_add_u64 v[140:141], v[140:141], 0, s[50:51]
	s_mov_b32 m0, s69
	s_nop 0
	global_load_lds_dwordx4 v[140:141], off
	s_barrier
	ds_read_b128 v[140:143], v136
	ds_read_b128 v[144:147], v136 offset:1024
	ds_read_b128 v[148:151], v136 offset:2048
	ds_read_b128 v[152:155], v136 offset:3072
	v_mov_b32_e32 v196, v129
	v_mov_b32_e32 v188, v130
	ds_read_b128 v[156:159], v134 offset:32768
	ds_read_b128 v[160:163], v134 offset:33792
	ds_read_b128 v[164:167], v133 offset:32768
	ds_read_b128 v[168:171], v133 offset:33792
	ds_read_b128 v[172:175], v132 offset:32768
	ds_read_b128 v[176:179], v132 offset:33792
	ds_read_b128 v[180:183], v131 offset:32768
	ds_read_b128 v[184:187], v131 offset:33792
	v_mov_b32_e32 v189, v197
	v_lshl_add_u64 v[190:191], s[8:9], 0, v[196:197]
	s_mov_b32 m0, s70
	v_lshl_add_u64 v[190:191], v[190:191], 0, s[90:91]
	v_lshl_add_u64 v[188:189], s[8:9], 0, v[188:189]
	v_lshl_add_u64 v[188:189], v[188:189], 0, s[90:91]
	s_mov_b32 m0, s71
	s_nop 0
	s_waitcnt lgkmcnt(8)
	s_barrier
	s_waitcnt lgkmcnt(0)
	s_setprio 1
	s_waitcnt lgkmcnt(0)
	v_mfma_f32_16x16x32_bf16 v[124:127], v[140:143], v[156:159], v[124:127]
	v_mfma_f32_16x16x32_bf16 v[120:123], v[148:151], v[156:159], v[120:123]
	v_mfma_f32_16x16x32_bf16 v[116:119], v[140:143], v[164:167], v[116:119]
	v_mfma_f32_16x16x32_bf16 v[112:115], v[148:151], v[164:167], v[112:115]
	v_mfma_f32_16x16x32_bf16 v[108:111], v[140:143], v[172:175], v[108:111]
	v_mfma_f32_16x16x32_bf16 v[104:107], v[148:151], v[172:175], v[104:107]
	v_mfma_f32_16x16x32_bf16 v[100:103], v[140:143], v[180:183], v[100:103]
	v_mfma_f32_16x16x32_bf16 v[96:99], v[148:151], v[180:183], v[96:99]
	v_mfma_f32_16x16x32_bf16 v[124:127], v[144:147], v[160:163], v[124:127]
	v_mfma_f32_16x16x32_bf16 v[120:123], v[152:155], v[160:163], v[120:123]
	v_mfma_f32_16x16x32_bf16 v[116:119], v[144:147], v[168:171], v[116:119]
	v_mfma_f32_16x16x32_bf16 v[112:115], v[152:155], v[168:171], v[112:115]
	v_mfma_f32_16x16x32_bf16 v[108:111], v[144:147], v[176:179], v[108:111]
	v_mfma_f32_16x16x32_bf16 v[104:107], v[152:155], v[176:179], v[104:107]
	v_mfma_f32_16x16x32_bf16 v[100:103], v[144:147], v[184:187], v[100:103]
	v_mfma_f32_16x16x32_bf16 v[96:99], v[152:155], v[184:187], v[96:99]
	s_setprio 0
	s_barrier
	v_mov_b32_e32 v196, v129
	v_mov_b32_e32 v210, v130
	ds_read_b128 v[188:191], v135
	ds_read_b128 v[192:195], v135 offset:1024
	ds_read_b128 v[202:205], v135 offset:2048
	ds_read_b128 v[206:209], v135 offset:3072
	v_mov_b32_e32 v211, v197
	v_lshl_add_u64 v[212:213], s[10:11], 0, v[196:197]
	s_mov_b32 m0, s28
	v_lshl_add_u64 v[212:213], v[212:213], 0, s[92:93]
	v_lshl_add_u64 v[210:211], s[10:11], 0, v[210:211]
	global_load_lds_dwordx4 v[212:213], off
	v_lshl_add_u64 v[210:211], v[210:211], 0, s[92:93]
	s_mov_b32 m0, s29
	s_nop 0
	global_load_lds_dwordx4 v[210:211], off
	s_barrier
	s_waitcnt lgkmcnt(0)
	s_setprio 1
	s_waitcnt lgkmcnt(0)
	v_mfma_f32_16x16x32_bf16 v[92:95], v[188:191], v[156:159], v[92:95]
	v_mfma_f32_16x16x32_bf16 v[88:91], v[202:205], v[156:159], v[88:91]
	v_mfma_f32_16x16x32_bf16 v[84:87], v[188:191], v[164:167], v[84:87]
	v_mfma_f32_16x16x32_bf16 v[80:83], v[202:205], v[164:167], v[80:83]
	v_mfma_f32_16x16x32_bf16 v[76:79], v[188:191], v[172:175], v[76:79]
	v_mfma_f32_16x16x32_bf16 v[72:75], v[202:205], v[172:175], v[72:75]
	v_mfma_f32_16x16x32_bf16 v[68:71], v[188:191], v[180:183], v[68:71]
	v_mfma_f32_16x16x32_bf16 v[64:67], v[202:205], v[180:183], v[64:67]
	v_mfma_f32_16x16x32_bf16 v[92:95], v[192:195], v[160:163], v[92:95]
	v_mfma_f32_16x16x32_bf16 v[88:91], v[206:209], v[160:163], v[88:91]
	v_mfma_f32_16x16x32_bf16 v[84:87], v[192:195], v[168:171], v[84:87]
	v_mfma_f32_16x16x32_bf16 v[80:83], v[206:209], v[168:171], v[80:83]
	v_mfma_f32_16x16x32_bf16 v[76:79], v[192:195], v[176:179], v[76:79]
	v_mfma_f32_16x16x32_bf16 v[72:75], v[206:209], v[176:179], v[72:75]
	v_mfma_f32_16x16x32_bf16 v[68:71], v[192:195], v[184:187], v[68:71]
	v_mfma_f32_16x16x32_bf16 v[64:67], v[206:209], v[184:187], v[64:67]
	s_setprio 0
	v_mov_b32_e32 v196, v129
	v_mov_b32_e32 v210, v130
	s_barrier
	v_mov_b32_e32 v211, v197
	v_lshl_add_u64 v[212:213], s[8:9], 0, v[196:197]
	s_mov_b32 m0, s72
	v_lshl_add_u64 v[212:213], v[212:213], 0, s[96:97]
	v_lshl_add_u64 v[210:211], s[8:9], 0, v[210:211]
	global_load_lds_dwordx4 v[212:213], off
	v_lshl_add_u64 v[210:211], v[210:211], 0, s[96:97]
	s_mov_b32 m0, s73
	s_nop 0
	global_load_lds_dwordx4 v[210:211], off
	s_waitcnt vmcnt(4)
	s_barrier
	v_mov_b32_e32 v196, v129
	v_mov_b32_e32 v140, v130
	v_mov_b32_e32 v141, v197
	v_lshl_add_u64 v[142:143], s[10:11], 0, v[196:197]
	s_mov_b32 m0, s33
	v_lshl_add_u64 v[142:143], v[142:143], 0, vcc
	v_lshl_add_u64 v[140:141], s[10:11], 0, v[140:141]
	global_load_lds_dwordx4 v[142:143], off
	v_lshl_add_u64 v[140:141], v[140:141], 0, vcc
	s_mov_b32 m0, s74
	s_nop 0
	global_load_lds_dwordx4 v[140:141], off
	s_barrier
	s_add_i32 s38, s38, 2
	s_add_u32 s6, s6, 0x100
	s_addc_u32 s7, s7, 0
	s_cmpk_lt_u32 s38, 0x54
	s_cbranch_scc1 .Lh2_loop
	s_add_u32 s4, s4, 0x2b80
	s_addc_u32 s5, s5, 0
	s_mov_b32 m0, s76
	ds_read_b128 v[140:143], v138
	ds_read_b128 v[144:147], v138 offset:1024
	ds_read_b128 v[148:151], v138 offset:2048
	ds_read_b128 v[152:155], v138 offset:3072
	ds_read_b128 v[156:159], v134
	ds_read_b128 v[160:163], v134 offset:1024
	ds_read_b128 v[164:167], v133
	ds_read_b128 v[168:171], v133 offset:1024
	ds_read_b128 v[172:175], v132
	ds_read_b128 v[176:179], v132 offset:1024
	ds_read_b128 v[180:183], v131
	ds_read_b128 v[184:187], v131 offset:1024
	s_nop 0
	s_mov_b32 m0, s75
	s_nop 0
	s_barrier
	s_waitcnt lgkmcnt(0)
	s_setprio 1
	s_waitcnt lgkmcnt(0)
	v_mfma_f32_16x16x32_bf16 v[124:127], v[140:143], v[156:159], v[124:127]
	v_mfma_f32_16x16x32_bf16 v[120:123], v[148:151], v[156:159], v[120:123]
	v_mfma_f32_16x16x32_bf16 v[116:119], v[140:143], v[164:167], v[116:119]
	v_mfma_f32_16x16x32_bf16 v[112:115], v[148:151], v[164:167], v[112:115]
	v_mfma_f32_16x16x32_bf16 v[108:111], v[140:143], v[172:175], v[108:111]
	v_mfma_f32_16x16x32_bf16 v[100:103], v[140:143], v[180:183], v[100:103]
	v_mfma_f32_16x16x32_bf16 v[96:99], v[148:151], v[180:183], v[96:99]
	v_mfma_f32_16x16x32_bf16 v[124:127], v[144:147], v[160:163], v[124:127]
	v_mfma_f32_16x16x32_bf16 v[120:123], v[152:155], v[160:163], v[120:123]
	v_mfma_f32_16x16x32_bf16 v[116:119], v[144:147], v[168:171], v[116:119]
	v_mfma_f32_16x16x32_bf16 v[112:115], v[152:155], v[168:171], v[112:115]
	v_mfma_f32_16x16x32_bf16 v[108:111], v[144:147], v[176:179], v[108:111]
	v_mfma_f32_16x16x32_bf16 v[104:107], v[148:151], v[172:175], v[104:107]
	v_mfma_f32_16x16x32_bf16 v[100:103], v[144:147], v[184:187], v[100:103]
	v_mfma_f32_16x16x32_bf16 v[96:99], v[152:155], v[184:187], v[96:99]
	v_mfma_f32_16x16x32_bf16 v[188:191], v[152:155], v[176:179], v[104:107]
	s_setprio 0
	s_barrier
	s_nop 2
	ds_read_b128 v[104:107], v137
	ds_read_b128 v[192:195], v137 offset:1024
	ds_read_b128 v[202:205], v137 offset:2048
	ds_read_b128 v[206:209], v137 offset:3072
	s_barrier
	s_waitcnt lgkmcnt(0)
	s_setprio 1
	s_waitcnt lgkmcnt(0)
	v_mfma_f32_16x16x32_bf16 v[92:95], v[104:107], v[156:159], v[92:95]
	v_mfma_f32_16x16x32_bf16 v[88:91], v[202:205], v[156:159], v[88:91]
	v_mfma_f32_16x16x32_bf16 v[80:83], v[202:205], v[164:167], v[80:83]
	v_mfma_f32_16x16x32_bf16 v[72:75], v[202:205], v[172:175], v[72:75]
	v_mfma_f32_16x16x32_bf16 v[64:67], v[202:205], v[180:183], v[64:67]
	v_mfma_f32_16x16x32_bf16 v[92:95], v[192:195], v[160:163], v[92:95]
	v_mfma_f32_16x16x32_bf16 v[88:91], v[206:209], v[160:163], v[88:91]
	v_mfma_f32_16x16x32_bf16 v[84:87], v[104:107], v[164:167], v[84:87]
	v_mfma_f32_16x16x32_bf16 v[80:83], v[206:209], v[168:171], v[80:83]
	v_mfma_f32_16x16x32_bf16 v[76:79], v[104:107], v[172:175], v[76:79]
	v_mfma_f32_16x16x32_bf16 v[72:75], v[206:209], v[176:179], v[72:75]
	v_mfma_f32_16x16x32_bf16 v[68:71], v[104:107], v[180:183], v[68:71]
	v_mfma_f32_16x16x32_bf16 v[64:67], v[206:209], v[184:187], v[64:67]
	v_mfma_f32_16x16x32_bf16 v[156:159], v[192:195], v[168:171], v[84:87]
	v_mfma_f32_16x16x32_bf16 v[160:163], v[192:195], v[176:179], v[76:79]
	v_mfma_f32_16x16x32_bf16 v[164:167], v[192:195], v[184:187], v[68:71]
	s_setprio 0
	s_barrier
	s_nop 1
	s_waitcnt vmcnt(2)
	s_barrier
	s_waitcnt lgkmcnt(0)
	s_setprio 1
	s_waitcnt lgkmcnt(0)
	s_setprio 0
	s_setprio 1
	s_setprio 0
	s_barrier
	ds_read_b128 v[16:19], v136
	ds_read_b128 v[180:183], v136 offset:1024
	ds_read_b128 v[184:187], v136 offset:2048
	ds_read_b128 v[192:195], v136 offset:3072
	ds_read_b128 v[0:3], v134 offset:32768
	ds_read_b128 v[4:7], v134 offset:33792
	ds_read_b128 v[8:11], v133 offset:32768
	ds_read_b128 v[12:15], v133 offset:33792
	ds_read_b128 v[44:47], v132 offset:32768
	ds_read_b128 v[202:205], v132 offset:33792
	ds_read_b128 v[206:209], v131 offset:32768
	ds_read_b128 v[222:225], v131 offset:33792
	s_waitcnt vmcnt(0)
	s_barrier
	s_waitcnt lgkmcnt(0)
	s_setprio 1
	s_waitcnt lgkmcnt(0)
	v_mfma_f32_16x16x32_bf16 v[28:31], v[16:19], v[0:3], v[124:127]
	v_mfma_f32_16x16x32_bf16 v[52:55], v[180:183], v[4:7], v[28:31]
	v_mfma_f32_16x16x32_bf16 v[28:31], v[184:187], v[0:3], v[120:123]
	v_mfma_f32_16x16x32_bf16 v[104:107], v[192:195], v[4:7], v[28:31]
	v_mfma_f32_16x16x32_bf16 v[28:31], v[16:19], v[8:11], v[116:119]
	v_mfma_f32_16x16x32_bf16 v[68:71], v[180:183], v[12:15], v[28:31]
	v_mfma_f32_16x16x32_bf16 v[28:31], v[184:187], v[8:11], v[112:115]
	v_mfma_f32_16x16x32_bf16 v[116:119], v[192:195], v[12:15], v[28:31]
	v_mfma_f32_16x16x32_bf16 v[28:31], v[16:19], v[44:47], v[108:111]
	v_mfma_f32_16x16x32_bf16 v[76:79], v[180:183], v[202:205], v[28:31]
	v_mfma_f32_16x16x32_bf16 v[28:31], v[184:187], v[44:47], v[188:191]
	v_mfma_f32_16x16x32_bf16 v[108:111], v[192:195], v[202:205], v[28:31]
	v_mfma_f32_16x16x32_bf16 v[28:31], v[16:19], v[206:209], v[100:103]
	v_mfma_f32_16x16x32_bf16 v[84:87], v[180:183], v[222:225], v[28:31]
	v_mfma_f32_16x16x32_bf16 v[28:31], v[184:187], v[206:209], v[96:99]
	v_mfma_f32_16x16x32_bf16 v[96:99], v[192:195], v[222:225], v[28:31]
	s_setprio 0
	s_barrier
	ds_read_b128 v[188:191], v135
	ds_read_b128 v[228:231], v135 offset:1024
	ds_read_b128 v[232:235], v135 offset:2048
	ds_read_b128 v[236:239], v135 offset:3072
	s_waitcnt vmcnt(0)
	s_barrier
	s_waitcnt lgkmcnt(0)
	s_setprio 1
	s_waitcnt lgkmcnt(0)
	v_mfma_f32_16x16x32_bf16 v[28:31], v[188:191], v[0:3], v[92:95]
	v_mfma_f32_16x16x32_bf16 v[0:3], v[232:235], v[0:3], v[88:91]
	v_mfma_f32_16x16x32_bf16 v[28:31], v[228:231], v[4:7], v[28:31]
	v_mfma_f32_16x16x32_bf16 v[0:3], v[236:239], v[4:7], v[0:3]
	v_mfma_f32_16x16x32_bf16 v[4:7], v[188:191], v[8:11], v[156:159]
	v_mfma_f32_16x16x32_bf16 v[36:39], v[228:231], v[12:15], v[4:7]
	v_mfma_f32_16x16x32_bf16 v[4:7], v[232:235], v[8:11], v[80:83]
	v_mfma_f32_16x16x32_bf16 v[4:7], v[236:239], v[12:15], v[4:7]
	v_mfma_f32_16x16x32_bf16 v[8:11], v[188:191], v[44:47], v[160:163]
	v_mfma_f32_16x16x32_bf16 v[12:15], v[188:191], v[206:209], v[164:167]
	v_mfma_f32_16x16x32_bf16 v[40:43], v[228:231], v[202:205], v[8:11]
	v_mfma_f32_16x16x32_bf16 v[8:11], v[232:235], v[44:47], v[72:75]
	v_mfma_f32_16x16x32_bf16 v[44:47], v[228:231], v[222:225], v[12:15]
	v_mfma_f32_16x16x32_bf16 v[12:15], v[232:235], v[206:209], v[64:67]
	v_mfma_f32_16x16x32_bf16 v[8:11], v[236:239], v[202:205], v[8:11]
	v_mfma_f32_16x16x32_bf16 v[12:15], v[236:239], v[222:225], v[12:15]
	s_setprio 0
	s_barrier
	s_barrier
	s_waitcnt lgkmcnt(0)
	s_setprio 1
	s_waitcnt lgkmcnt(0)
	s_setprio 0
	s_setprio 1
	s_setprio 0
	s_movk_i32 s4, 0x100
	v_cmp_gt_u32_e32 vcc, s4, v128
	s_barrier
	s_and_saveexec_b64 s[4:5], vcc
	s_cbranch_execz .Lh2_epi
	s_barrier

.Lhf_192:
	ds_read_b128 v[140:143], v129
	ds_read_b128 v[144:147], v129 offset:1024
	ds_read_b128 v[148:151], v129 offset:2048
	ds_read_b128 v[152:155], v129 offset:3072
	s_add_u32 s28, s56, s4
	v_mov_b32_e32 v196, v128
	v_mov_b32_e32 v188, v130
	s_addc_u32 s29, s57, s5
	ds_read_b128 v[156:159], v136
	ds_read_b128 v[160:163], v136 offset:1024
	ds_read_b128 v[164:167], v135
	ds_read_b128 v[168:171], v135 offset:1024
	ds_read_b128 v[172:175], v134
	ds_read_b128 v[176:179], v134 offset:1024
	ds_read_b128 v[180:183], v133
	ds_read_b128 v[184:187], v133 offset:1024
	s_add_i32 s40, s52, 0xc000
	v_lshl_add_u64 v[190:191], s[28:29], 0, v[196:197]
	v_mov_b32_e32 v189, v197
	v_lshl_add_u64 v[190:191], v[190:191], 0, s[44:45]
	s_mov_b32 m0, s40
	v_lshl_add_u64 v[188:189], s[28:29], 0, v[188:189]
	s_add_i32 s39, s52, 0xe000
	v_lshl_add_u64 v[188:189], v[188:189], 0, s[44:45]
	s_mov_b32 m0, s39
	s_nop 0
	s_waitcnt lgkmcnt(8)
	s_barrier
	s_waitcnt lgkmcnt(0)
	s_setprio 1
	s_waitcnt lgkmcnt(0)
	v_mfma_f32_16x16x32_bf16 v[124:127], v[140:143], v[156:159], v[124:127]
	v_mfma_f32_16x16x32_bf16 v[120:123], v[148:151], v[156:159], v[120:123]
	v_mfma_f32_16x16x32_bf16 v[116:119], v[140:143], v[164:167], v[116:119]
	v_mfma_f32_16x16x32_bf16 v[112:115], v[148:151], v[164:167], v[112:115]
	v_mfma_f32_16x16x32_bf16 v[108:111], v[140:143], v[172:175], v[108:111]
	v_mfma_f32_16x16x32_bf16 v[104:107], v[148:151], v[172:175], v[104:107]
	v_mfma_f32_16x16x32_bf16 v[100:103], v[140:143], v[180:183], v[100:103]
	v_mfma_f32_16x16x32_bf16 v[96:99], v[148:151], v[180:183], v[96:99]
	v_mfma_f32_16x16x32_bf16 v[124:127], v[144:147], v[160:163], v[124:127]
	v_mfma_f32_16x16x32_bf16 v[120:123], v[152:155], v[160:163], v[120:123]
	v_mfma_f32_16x16x32_bf16 v[116:119], v[144:147], v[168:171], v[116:119]
	v_mfma_f32_16x16x32_bf16 v[112:115], v[152:155], v[168:171], v[112:115]
	v_mfma_f32_16x16x32_bf16 v[108:111], v[144:147], v[176:179], v[108:111]
	v_mfma_f32_16x16x32_bf16 v[104:107], v[152:155], v[176:179], v[104:107]
	v_mfma_f32_16x16x32_bf16 v[100:103], v[144:147], v[184:187], v[100:103]
	v_mfma_f32_16x16x32_bf16 v[96:99], v[152:155], v[184:187], v[96:99]
	s_setprio 0
	s_barrier
	s_add_u32 s58, s56, s36
	v_mov_b32_e32 v196, v128
	v_mov_b32_e32 v210, v130
	s_addc_u32 s59, s57, s37
	ds_read_b128 v[188:191], v139
	ds_read_b128 v[192:195], v139 offset:1024
	ds_read_b128 v[202:205], v139 offset:2048
	ds_read_b128 v[206:209], v139 offset:3072
	v_mov_b32_e32 v211, v197
	v_lshl_add_u64 v[212:213], s[58:59], 0, v[196:197]
	v_lshl_add_u64 v[212:213], v[212:213], 0, s[46:47]
	s_add_i32 m0, s52, 0x10000
	v_lshl_add_u64 v[210:211], s[58:59], 0, v[210:211]
	global_load_lds_dwordx4 v[212:213], off
	v_lshl_add_u64 v[210:211], v[210:211], 0, s[46:47]
	s_add_i32 m0, s52, 0x12000
	s_nop 0
	global_load_lds_dwordx4 v[210:211], off
	s_barrier
	s_waitcnt lgkmcnt(0)
	s_setprio 1
	s_waitcnt lgkmcnt(0)
	v_mfma_f32_16x16x32_bf16 v[92:95], v[188:191], v[156:159], v[92:95]
	v_mfma_f32_16x16x32_bf16 v[88:91], v[202:205], v[156:159], v[88:91]
	v_mfma_f32_16x16x32_bf16 v[84:87], v[188:191], v[164:167], v[84:87]
	v_mfma_f32_16x16x32_bf16 v[80:83], v[202:205], v[164:167], v[80:83]
	v_mfma_f32_16x16x32_bf16 v[76:79], v[188:191], v[172:175], v[76:79]
	v_mfma_f32_16x16x32_bf16 v[72:75], v[202:205], v[172:175], v[72:75]
	v_mfma_f32_16x16x32_bf16 v[68:71], v[188:191], v[180:183], v[68:71]
	v_mfma_f32_16x16x32_bf16 v[64:67], v[202:205], v[180:183], v[64:67]
	v_mfma_f32_16x16x32_bf16 v[92:95], v[192:195], v[160:163], v[92:95]
	v_mfma_f32_16x16x32_bf16 v[88:91], v[206:209], v[160:163], v[88:91]
	v_mfma_f32_16x16x32_bf16 v[84:87], v[192:195], v[168:171], v[84:87]
	v_mfma_f32_16x16x32_bf16 v[80:83], v[206:209], v[168:171], v[80:83]
	v_mfma_f32_16x16x32_bf16 v[76:79], v[192:195], v[176:179], v[76:79]
	v_mfma_f32_16x16x32_bf16 v[72:75], v[206:209], v[176:179], v[72:75]
	v_mfma_f32_16x16x32_bf16 v[68:71], v[192:195], v[184:187], v[68:71]
	v_mfma_f32_16x16x32_bf16 v[64:67], v[206:209], v[184:187], v[64:67]
	s_setprio 0
	v_mov_b32_e32 v196, v128
	v_mov_b32_e32 v210, v130
	s_barrier
	v_mov_b32_e32 v211, v197
	v_lshl_add_u64 v[212:213], s[28:29], 0, v[196:197]
	s_mov_b32 m0, s52
	v_lshl_add_u64 v[212:213], v[212:213], 0, s[48:49]
	v_lshl_add_u64 v[210:211], s[28:29], 0, v[210:211]
	global_load_lds_dwordx4 v[212:213], off
	v_lshl_add_u64 v[210:211], v[210:211], 0, s[48:49]
	s_add_i32 m0, s52, 0x2000
	s_nop 0
	global_load_lds_dwordx4 v[210:211], off
	s_waitcnt vmcnt(4)
	s_barrier
	v_mov_b32_e32 v196, v128
	v_mov_b32_e32 v140, v130
	v_mov_b32_e32 v141, v197
	v_lshl_add_u64 v[142:143], s[58:59], 0, v[196:197]
	v_lshl_add_u64 v[142:143], v[142:143], 0, s[50:51]
	s_add_i32 m0, s52, 0x14000
	v_lshl_add_u64 v[140:141], s[58:59], 0, v[140:141]
	global_load_lds_dwordx4 v[142:143], off
	v_lshl_add_u64 v[140:141], v[140:141], 0, s[50:51]
	s_add_i32 m0, s52, 0x16000
	s_nop 0
	global_load_lds_dwordx4 v[140:141], off
	s_barrier
	ds_read_b128 v[140:143], v138
	ds_read_b128 v[144:147], v138 offset:1024
	ds_read_b128 v[148:151], v138 offset:2048
	ds_read_b128 v[152:155], v138 offset:3072
	v_mov_b32_e32 v196, v128
	v_mov_b32_e32 v188, v130
	ds_read_b128 v[156:159], v136 offset:32768
	ds_read_b128 v[160:163], v136 offset:33792
	ds_read_b128 v[164:167], v135 offset:32768
	ds_read_b128 v[168:171], v135 offset:33792
	ds_read_b128 v[172:175], v134 offset:32768
	ds_read_b128 v[176:179], v134 offset:33792
	ds_read_b128 v[180:183], v133 offset:32768
	ds_read_b128 v[184:187], v133 offset:33792
	v_mov_b32_e32 v189, v197
	v_lshl_add_u64 v[190:191], s[28:29], 0, v[196:197]
	v_lshl_add_u64 v[190:191], v[190:191], 0, s[54:55]
	s_add_i32 m0, s52, 0x4000
	v_lshl_add_u64 v[188:189], s[28:29], 0, v[188:189]
	v_lshl_add_u64 v[188:189], v[188:189], 0, s[54:55]
	s_add_i32 m0, s52, 0x6000
	s_nop 0
	s_waitcnt lgkmcnt(8)
	s_barrier
	s_waitcnt lgkmcnt(0)
	s_setprio 1
	s_waitcnt lgkmcnt(0)
	v_mfma_f32_16x16x32_bf16 v[124:127], v[140:143], v[156:159], v[124:127]
	v_mfma_f32_16x16x32_bf16 v[120:123], v[148:151], v[156:159], v[120:123]
	v_mfma_f32_16x16x32_bf16 v[116:119], v[140:143], v[164:167], v[116:119]
	v_mfma_f32_16x16x32_bf16 v[112:115], v[148:151], v[164:167], v[112:115]
	v_mfma_f32_16x16x32_bf16 v[108:111], v[140:143], v[172:175], v[108:111]
	v_mfma_f32_16x16x32_bf16 v[104:107], v[148:151], v[172:175], v[104:107]
	v_mfma_f32_16x16x32_bf16 v[100:103], v[140:143], v[180:183], v[100:103]
	v_mfma_f32_16x16x32_bf16 v[96:99], v[148:151], v[180:183], v[96:99]
	v_mfma_f32_16x16x32_bf16 v[124:127], v[144:147], v[160:163], v[124:127]
	v_mfma_f32_16x16x32_bf16 v[120:123], v[152:155], v[160:163], v[120:123]
	v_mfma_f32_16x16x32_bf16 v[116:119], v[144:147], v[168:171], v[116:119]
	v_mfma_f32_16x16x32_bf16 v[112:115], v[152:155], v[168:171], v[112:115]
	v_mfma_f32_16x16x32_bf16 v[108:111], v[144:147], v[176:179], v[108:111]
	v_mfma_f32_16x16x32_bf16 v[104:107], v[152:155], v[176:179], v[104:107]
	v_mfma_f32_16x16x32_bf16 v[100:103], v[144:147], v[184:187], v[100:103]
	v_mfma_f32_16x16x32_bf16 v[96:99], v[152:155], v[184:187], v[96:99]
	s_setprio 0
	s_barrier
	v_mov_b32_e32 v196, v128
	v_mov_b32_e32 v210, v130
	ds_read_b128 v[188:191], v137
	ds_read_b128 v[192:195], v137 offset:1024
	ds_read_b128 v[202:205], v137 offset:2048
	ds_read_b128 v[206:209], v137 offset:3072
	v_mov_b32_e32 v211, v197
	v_lshl_add_u64 v[212:213], s[58:59], 0, v[196:197]
	s_mov_b32 m0, s7
	v_lshl_add_u64 v[212:213], v[212:213], 0, s[68:69]
	v_lshl_add_u64 v[210:211], s[58:59], 0, v[210:211]
	global_load_lds_dwordx4 v[212:213], off
	v_lshl_add_u64 v[210:211], v[210:211], 0, s[68:69]
	s_mov_b32 m0, s53
	s_nop 0
	global_load_lds_dwordx4 v[210:211], off
	s_barrier
	s_waitcnt lgkmcnt(0)
	s_setprio 1
	s_waitcnt lgkmcnt(0)
	v_mfma_f32_16x16x32_bf16 v[92:95], v[188:191], v[156:159], v[92:95]
	v_mfma_f32_16x16x32_bf16 v[88:91], v[202:205], v[156:159], v[88:91]
	v_mfma_f32_16x16x32_bf16 v[84:87], v[188:191], v[164:167], v[84:87]
	v_mfma_f32_16x16x32_bf16 v[80:83], v[202:205], v[164:167], v[80:83]
	v_mfma_f32_16x16x32_bf16 v[76:79], v[188:191], v[172:175], v[76:79]
	v_mfma_f32_16x16x32_bf16 v[72:75], v[202:205], v[172:175], v[72:75]
	v_mfma_f32_16x16x32_bf16 v[68:71], v[188:191], v[180:183], v[68:71]
	v_mfma_f32_16x16x32_bf16 v[64:67], v[202:205], v[180:183], v[64:67]
	v_mfma_f32_16x16x32_bf16 v[92:95], v[192:195], v[160:163], v[92:95]
	v_mfma_f32_16x16x32_bf16 v[88:91], v[206:209], v[160:163], v[88:91]
	v_mfma_f32_16x16x32_bf16 v[84:87], v[192:195], v[168:171], v[84:87]
	v_mfma_f32_16x16x32_bf16 v[80:83], v[206:209], v[168:171], v[80:83]
	v_mfma_f32_16x16x32_bf16 v[76:79], v[192:195], v[176:179], v[76:79]
	v_mfma_f32_16x16x32_bf16 v[72:75], v[206:209], v[176:179], v[72:75]
	v_mfma_f32_16x16x32_bf16 v[68:71], v[192:195], v[184:187], v[68:71]
	v_mfma_f32_16x16x32_bf16 v[64:67], v[206:209], v[184:187], v[64:67]
	s_setprio 0
	v_mov_b32_e32 v196, v128
	v_mov_b32_e32 v210, v130
	s_barrier
	v_mov_b32_e32 v211, v197
	v_lshl_add_u64 v[212:213], s[28:29], 0, v[196:197]
	s_mov_b32 m0, s9
	v_lshl_add_u64 v[212:213], v[212:213], 0, s[70:71]
	v_lshl_add_u64 v[210:211], s[28:29], 0, v[210:211]
	global_load_lds_dwordx4 v[212:213], off
	v_lshl_add_u64 v[210:211], v[210:211], 0, s[70:71]
	s_mov_b32 m0, s33
	s_nop 0
	global_load_lds_dwordx4 v[210:211], off
	s_waitcnt vmcnt(4)
	s_barrier
	v_mov_b32_e32 v196, v128
	v_mov_b32_e32 v140, v130
	v_mov_b32_e32 v141, v197
	v_lshl_add_u64 v[142:143], s[58:59], 0, v[196:197]
	s_mov_b32 m0, s65
	v_lshl_add_u64 v[142:143], v[142:143], 0, s[72:73]
	v_lshl_add_u64 v[140:141], s[58:59], 0, v[140:141]
	global_load_lds_dwordx4 v[142:143], off
	v_lshl_add_u64 v[140:141], v[140:141], 0, s[72:73]
	s_mov_b32 m0, s66
	s_nop 0
	global_load_lds_dwordx4 v[140:141], off
	s_barrier
	s_add_i32 s38, s38, 2
	s_add_u32 s56, s56, 0x100
	s_addc_u32 s57, s57, 0
	s_cmp_lt_u32 s38, 28
	s_cbranch_scc1 .Lhf_192
	s_lshl_b64 s[4:5], s[10:11], 12
	v_readlane_b32 s10, v254, 12
	v_readlane_b32 s11, v254, 13
	s_add_u32 s4, s10, s4
	s_addc_u32 s5, s11, s5
	ds_read_b128 v[140:143], v129
	ds_read_b128 v[144:147], v129 offset:1024
	ds_read_b128 v[148:151], v129 offset:2048
	ds_read_b128 v[152:155], v129 offset:3072
	ds_read_b128 v[156:159], v136
	ds_read_b128 v[160:163], v136 offset:1024
	ds_read_b128 v[164:167], v135
	ds_read_b128 v[168:171], v135 offset:1024
	ds_read_b128 v[172:175], v134
	ds_read_b128 v[176:179], v134 offset:1024
	ds_read_b128 v[180:183], v133
	ds_read_b128 v[184:187], v133 offset:1024
	v_mov_b32_e32 v129, v197
	v_lshl_add_u64 v[128:129], s[4:5], 0, v[128:129]
	s_mov_b64 s[10:11], 0xf80
	s_mov_b32 m0, s40
	v_lshl_add_u64 v[128:129], v[128:129], 0, s[10:11]
	v_mov_b32_e32 v131, v197
	v_lshl_add_u64 v[128:129], s[4:5], 0, v[130:131]
	v_lshl_add_u64 v[128:129], v[128:129], 0, s[10:11]
	s_mov_b32 m0, s39
	s_nop 0
	s_barrier
	s_waitcnt lgkmcnt(0)
	s_setprio 1
	s_waitcnt lgkmcnt(0)
	v_mfma_f32_16x16x32_bf16 v[124:127], v[140:143], v[156:159], v[124:127]
	v_mfma_f32_16x16x32_bf16 v[116:119], v[140:143], v[164:167], v[116:119]
	v_mfma_f32_16x16x32_bf16 v[112:115], v[148:151], v[164:167], v[112:115]
	v_mfma_f32_16x16x32_bf16 v[108:111], v[140:143], v[172:175], v[108:111]
	v_mfma_f32_16x16x32_bf16 v[104:107], v[148:151], v[172:175], v[104:107]
	v_mfma_f32_16x16x32_bf16 v[100:103], v[140:143], v[180:183], v[100:103]
	v_mfma_f32_16x16x32_bf16 v[96:99], v[148:151], v[180:183], v[96:99]
	v_mfma_f32_16x16x32_bf16 v[124:127], v[144:147], v[160:163], v[124:127]
	v_mfma_f32_16x16x32_bf16 v[120:123], v[148:151], v[156:159], v[120:123]
	v_mfma_f32_16x16x32_bf16 v[116:119], v[144:147], v[168:171], v[116:119]
	v_mfma_f32_16x16x32_bf16 v[112:115], v[152:155], v[168:171], v[112:115]
	v_mfma_f32_16x16x32_bf16 v[108:111], v[144:147], v[176:179], v[108:111]
	v_mfma_f32_16x16x32_bf16 v[104:107], v[152:155], v[176:179], v[104:107]
	v_mfma_f32_16x16x32_bf16 v[100:103], v[144:147], v[184:187], v[100:103]
	v_mfma_f32_16x16x32_bf16 v[96:99], v[152:155], v[184:187], v[96:99]
	v_mfma_f32_16x16x32_bf16 v[128:131], v[152:155], v[160:163], v[120:123]
	s_setprio 0
	s_barrier
	s_nop 0
	ds_read_b128 v[120:123], v139
	ds_read_b128 v[188:191], v139 offset:1024
	ds_read_b128 v[192:195], v139 offset:2048
	ds_read_b128 v[202:205], v139 offset:3072
	s_barrier
	s_waitcnt lgkmcnt(0)
	s_setprio 1
	s_waitcnt lgkmcnt(0)
	v_mfma_f32_16x16x32_bf16 v[76:79], v[120:123], v[172:175], v[76:79]
	v_mfma_f32_16x16x32_bf16 v[68:71], v[120:123], v[180:183], v[68:71]
	v_mfma_f32_16x16x32_bf16 v[64:67], v[192:195], v[180:183], v[64:67]
	v_mfma_f32_16x16x32_bf16 v[92:95], v[120:123], v[156:159], v[92:95]
	v_mfma_f32_16x16x32_bf16 v[88:91], v[192:195], v[156:159], v[88:91]
	v_mfma_f32_16x16x32_bf16 v[84:87], v[120:123], v[164:167], v[84:87]
	v_mfma_f32_16x16x32_bf16 v[80:83], v[192:195], v[164:167], v[80:83]
	v_mfma_f32_16x16x32_bf16 v[76:79], v[188:191], v[176:179], v[76:79]
	v_mfma_f32_16x16x32_bf16 v[72:75], v[192:195], v[172:175], v[72:75]
	v_mfma_f32_16x16x32_bf16 v[68:71], v[188:191], v[184:187], v[68:71]
	v_mfma_f32_16x16x32_bf16 v[64:67], v[202:205], v[184:187], v[64:67]
	v_mfma_f32_16x16x32_bf16 v[206:209], v[188:191], v[160:163], v[92:95]
	v_mfma_f32_16x16x32_bf16 v[156:159], v[202:205], v[160:163], v[88:91]
	v_mfma_f32_16x16x32_bf16 v[160:163], v[188:191], v[168:171], v[84:87]
	v_mfma_f32_16x16x32_bf16 v[164:167], v[202:205], v[168:171], v[80:83]
	v_mfma_f32_16x16x32_bf16 v[168:171], v[202:205], v[176:179], v[72:75]
	s_setprio 0
	s_barrier
	s_nop 0
	s_waitcnt vmcnt(2)
	s_barrier
	s_waitcnt lgkmcnt(0)
	s_setprio 1
	s_waitcnt lgkmcnt(0)
	s_setprio 0
	s_setprio 1
	s_setprio 0
	s_barrier
	s_nop 0
	ds_read_b128 v[8:11], v138
	ds_read_b128 v[16:19], v138 offset:1024
	ds_read_b128 v[176:179], v138 offset:2048
	ds_read_b128 v[180:183], v138 offset:3072
	ds_read_b128 v[20:23], v136 offset:32768
	ds_read_b128 v[24:27], v136 offset:33792
	ds_read_b128 v[28:31], v135 offset:32768
	ds_read_b128 v[56:59], v135 offset:33792
	ds_read_b128 v[188:191], v134 offset:32768
	ds_read_b128 v[192:195], v134 offset:33792
	ds_read_b128 v[202:205], v133 offset:32768
	ds_read_b128 v[210:213], v133 offset:33792
	s_waitcnt vmcnt(0)
	s_barrier
	s_waitcnt lgkmcnt(0)
	s_setprio 1
	s_waitcnt lgkmcnt(0)
	v_mfma_f32_16x16x32_bf16 v[72:75], v[8:11], v[20:23], v[124:127]
	v_mfma_f32_16x16x32_bf16 v[120:123], v[16:19], v[24:27], v[72:75]
	v_mfma_f32_16x16x32_bf16 v[72:75], v[176:179], v[20:23], v[128:131]
	v_mfma_f32_16x16x32_bf16 v[124:127], v[180:183], v[24:27], v[72:75]
	v_mfma_f32_16x16x32_bf16 v[72:75], v[8:11], v[28:31], v[116:119]
	v_mfma_f32_16x16x32_bf16 v[116:119], v[16:19], v[56:59], v[72:75]
	v_mfma_f32_16x16x32_bf16 v[72:75], v[176:179], v[28:31], v[112:115]
	v_mfma_f32_16x16x32_bf16 v[112:115], v[180:183], v[56:59], v[72:75]
	v_mfma_f32_16x16x32_bf16 v[72:75], v[8:11], v[188:191], v[108:111]
	v_mfma_f32_16x16x32_bf16 v[88:91], v[16:19], v[192:195], v[72:75]
	v_mfma_f32_16x16x32_bf16 v[72:75], v[176:179], v[188:191], v[104:107]
	v_mfma_f32_16x16x32_bf16 v[92:95], v[180:183], v[192:195], v[72:75]
	v_mfma_f32_16x16x32_bf16 v[72:75], v[8:11], v[202:205], v[100:103]
	v_mfma_f32_16x16x32_bf16 v[84:87], v[16:19], v[210:213], v[72:75]
	v_mfma_f32_16x16x32_bf16 v[72:75], v[176:179], v[202:205], v[96:99]
	v_mfma_f32_16x16x32_bf16 v[80:83], v[180:183], v[210:213], v[72:75]
	s_setprio 0
	s_barrier
	ds_read_b128 v[128:131], v137
	ds_read_b128 v[214:217], v137 offset:1024
	ds_read_b128 v[218:221], v137 offset:2048
	ds_read_b128 v[222:225], v137 offset:3072
	s_waitcnt vmcnt(0)
	s_barrier
	s_waitcnt lgkmcnt(0)
	s_setprio 1
	s_waitcnt lgkmcnt(0)
	v_mfma_f32_16x16x32_bf16 v[72:75], v[128:131], v[20:23], v[206:209]
	v_mfma_f32_16x16x32_bf16 v[20:23], v[218:221], v[20:23], v[156:159]
	v_mfma_f32_16x16x32_bf16 v[108:111], v[222:225], v[24:27], v[20:23]
	v_mfma_f32_16x16x32_bf16 v[20:23], v[128:131], v[28:31], v[160:163]
	v_mfma_f32_16x16x32_bf16 v[100:103], v[214:217], v[56:59], v[20:23]
	v_mfma_f32_16x16x32_bf16 v[20:23], v[218:221], v[28:31], v[164:167]
	v_mfma_f32_16x16x32_bf16 v[96:99], v[222:225], v[56:59], v[20:23]
	v_mfma_f32_16x16x32_bf16 v[20:23], v[128:131], v[188:191], v[76:79]
	v_mfma_f32_16x16x32_bf16 v[104:107], v[214:217], v[24:27], v[72:75]
	v_mfma_f32_16x16x32_bf16 v[72:75], v[214:217], v[192:195], v[20:23]
	v_mfma_f32_16x16x32_bf16 v[20:23], v[218:221], v[188:191], v[168:171]
	v_mfma_f32_16x16x32_bf16 v[76:79], v[222:225], v[192:195], v[20:23]
	v_mfma_f32_16x16x32_bf16 v[20:23], v[128:131], v[202:205], v[68:71]
	v_mfma_f32_16x16x32_bf16 v[68:71], v[214:217], v[210:213], v[20:23]
	v_mfma_f32_16x16x32_bf16 v[20:23], v[218:221], v[202:205], v[64:67]
	v_mfma_f32_16x16x32_bf16 v[64:67], v[222:225], v[210:213], v[20:23]
	s_setprio 0
	s_barrier
	s_barrier
	s_waitcnt lgkmcnt(0)
	s_setprio 1
	s_waitcnt lgkmcnt(0)
	s_setprio 0
	s_setprio 1
	s_setprio 0
	s_movk_i32 s4, 0x100
	v_cmp_gt_u32_e32 vcc, s4, v132
	s_barrier
	s_and_saveexec_b64 s[4:5], vcc
	s_cbranch_execz .Lhf_195
	s_barrier

.Lh1_loop:
	ds_read_b128 v[140:143], v129
	ds_read_b128 v[144:147], v129 offset:1024
	ds_read_b128 v[148:151], v129 offset:2048
	ds_read_b128 v[152:155], v129 offset:3072
	s_add_u32 s28, s60, s56
	v_mov_b32_e32 v196, v128
	v_mov_b32_e32 v188, v130
	s_addc_u32 s29, s61, s57
	ds_read_b128 v[156:159], v136
	ds_read_b128 v[160:163], v136 offset:1024
	ds_read_b128 v[164:167], v135
	ds_read_b128 v[168:171], v135 offset:1024
	ds_read_b128 v[172:175], v134
	ds_read_b128 v[176:179], v134 offset:1024
	ds_read_b128 v[180:183], v133
	ds_read_b128 v[184:187], v133 offset:1024
	s_add_i32 s40, s53, 0xc000
	v_lshl_add_u64 v[190:191], s[28:29], 0, v[196:197]
	v_mov_b32_e32 v189, v197
	v_lshl_add_u64 v[190:191], v[190:191], 0, s[44:45]
	s_mov_b32 m0, s40
	v_lshl_add_u64 v[188:189], s[28:29], 0, v[188:189]
	s_add_i32 s39, s53, 0xe000
	v_lshl_add_u64 v[188:189], v[188:189], 0, s[44:45]
	s_mov_b32 m0, s39
	s_nop 0
	s_waitcnt lgkmcnt(8)
	s_barrier
	s_waitcnt lgkmcnt(0)
	s_setprio 1
	s_waitcnt lgkmcnt(0)
	v_mfma_f32_16x16x32_bf16 v[124:127], v[140:143], v[156:159], v[124:127]
	v_mfma_f32_16x16x32_bf16 v[120:123], v[148:151], v[156:159], v[120:123]
	v_mfma_f32_16x16x32_bf16 v[116:119], v[140:143], v[164:167], v[116:119]
	v_mfma_f32_16x16x32_bf16 v[112:115], v[148:151], v[164:167], v[112:115]
	v_mfma_f32_16x16x32_bf16 v[108:111], v[140:143], v[172:175], v[108:111]
	v_mfma_f32_16x16x32_bf16 v[104:107], v[148:151], v[172:175], v[104:107]
	v_mfma_f32_16x16x32_bf16 v[100:103], v[140:143], v[180:183], v[100:103]
	v_mfma_f32_16x16x32_bf16 v[96:99], v[148:151], v[180:183], v[96:99]
	v_mfma_f32_16x16x32_bf16 v[124:127], v[144:147], v[160:163], v[124:127]
	v_mfma_f32_16x16x32_bf16 v[120:123], v[152:155], v[160:163], v[120:123]
	v_mfma_f32_16x16x32_bf16 v[116:119], v[144:147], v[168:171], v[116:119]
	v_mfma_f32_16x16x32_bf16 v[112:115], v[152:155], v[168:171], v[112:115]
	v_mfma_f32_16x16x32_bf16 v[108:111], v[144:147], v[176:179], v[108:111]
	v_mfma_f32_16x16x32_bf16 v[104:107], v[152:155], v[176:179], v[104:107]
	v_mfma_f32_16x16x32_bf16 v[100:103], v[144:147], v[184:187], v[100:103]
	v_mfma_f32_16x16x32_bf16 v[96:99], v[152:155], v[184:187], v[96:99]
	s_setprio 0
	s_barrier
	s_add_u32 s62, s60, s36
	v_mov_b32_e32 v196, v128
	v_mov_b32_e32 v210, v130
	s_addc_u32 s63, s61, s37
	ds_read_b128 v[188:191], v139
	ds_read_b128 v[192:195], v139 offset:1024
	ds_read_b128 v[202:205], v139 offset:2048
	ds_read_b128 v[206:209], v139 offset:3072
	v_mov_b32_e32 v211, v197
	v_lshl_add_u64 v[212:213], s[62:63], 0, v[196:197]
	s_mov_b32 m0, s68
	v_lshl_add_u64 v[212:213], v[212:213], 0, s[46:47]
	v_lshl_add_u64 v[210:211], s[62:63], 0, v[210:211]
	global_load_lds_dwordx4 v[212:213], off
	v_lshl_add_u64 v[210:211], v[210:211], 0, s[46:47]
	s_mov_b32 m0, s69
	s_nop 0
	global_load_lds_dwordx4 v[210:211], off
	s_barrier
	s_waitcnt lgkmcnt(0)
	s_setprio 1
	s_waitcnt lgkmcnt(0)
	v_mfma_f32_16x16x32_bf16 v[92:95], v[188:191], v[156:159], v[92:95]
	v_mfma_f32_16x16x32_bf16 v[88:91], v[202:205], v[156:159], v[88:91]
	v_mfma_f32_16x16x32_bf16 v[84:87], v[188:191], v[164:167], v[84:87]
	v_mfma_f32_16x16x32_bf16 v[80:83], v[202:205], v[164:167], v[80:83]
	v_mfma_f32_16x16x32_bf16 v[76:79], v[188:191], v[172:175], v[76:79]
	v_mfma_f32_16x16x32_bf16 v[72:75], v[202:205], v[172:175], v[72:75]
	v_mfma_f32_16x16x32_bf16 v[68:71], v[188:191], v[180:183], v[68:71]
	v_mfma_f32_16x16x32_bf16 v[64:67], v[202:205], v[180:183], v[64:67]
	v_mfma_f32_16x16x32_bf16 v[92:95], v[192:195], v[160:163], v[92:95]
	v_mfma_f32_16x16x32_bf16 v[88:91], v[206:209], v[160:163], v[88:91]
	v_mfma_f32_16x16x32_bf16 v[84:87], v[192:195], v[168:171], v[84:87]
	v_mfma_f32_16x16x32_bf16 v[80:83], v[206:209], v[168:171], v[80:83]
	v_mfma_f32_16x16x32_bf16 v[76:79], v[192:195], v[176:179], v[76:79]
	v_mfma_f32_16x16x32_bf16 v[72:75], v[206:209], v[176:179], v[72:75]
	v_mfma_f32_16x16x32_bf16 v[68:71], v[192:195], v[184:187], v[68:71]
	v_mfma_f32_16x16x32_bf16 v[64:67], v[206:209], v[184:187], v[64:67]
	s_setprio 0
	v_mov_b32_e32 v196, v128
	v_mov_b32_e32 v210, v130
	s_barrier
	v_mov_b32_e32 v211, v197
	v_lshl_add_u64 v[212:213], s[28:29], 0, v[196:197]
	s_mov_b32 m0, s53
	v_lshl_add_u64 v[212:213], v[212:213], 0, s[48:49]
	v_lshl_add_u64 v[210:211], s[28:29], 0, v[210:211]
	global_load_lds_dwordx4 v[212:213], off
	v_lshl_add_u64 v[210:211], v[210:211], 0, s[48:49]
	s_mov_b32 m0, s11
	s_nop 0
	global_load_lds_dwordx4 v[210:211], off
	s_waitcnt vmcnt(4)
	s_barrier
	v_mov_b32_e32 v196, v128
	v_mov_b32_e32 v140, v130
	v_mov_b32_e32 v141, v197
	v_lshl_add_u64 v[142:143], s[62:63], 0, v[196:197]
	s_mov_b32 m0, s9
	v_lshl_add_u64 v[142:143], v[142:143], 0, s[50:51]
	v_lshl_add_u64 v[140:141], s[62:63], 0, v[140:141]
	global_load_lds_dwordx4 v[142:143], off
	v_lshl_add_u64 v[140:141], v[140:141], 0, s[50:51]
	s_mov_b32 m0, s70
	s_nop 0
	global_load_lds_dwordx4 v[140:141], off
	s_barrier
	ds_read_b128 v[140:143], v138
	ds_read_b128 v[144:147], v138 offset:1024
	ds_read_b128 v[148:151], v138 offset:2048
	ds_read_b128 v[152:155], v138 offset:3072
	v_mov_b32_e32 v196, v128
	v_mov_b32_e32 v188, v130
	ds_read_b128 v[156:159], v136 offset:32768
	ds_read_b128 v[160:163], v136 offset:33792
	ds_read_b128 v[164:167], v135 offset:32768
	ds_read_b128 v[168:171], v135 offset:33792
	ds_read_b128 v[172:175], v134 offset:32768
	ds_read_b128 v[176:179], v134 offset:33792
	ds_read_b128 v[180:183], v133 offset:32768
	ds_read_b128 v[184:187], v133 offset:33792
	v_mov_b32_e32 v189, v197
	v_lshl_add_u64 v[190:191], s[28:29], 0, v[196:197]
	s_mov_b32 m0, s71
	v_lshl_add_u64 v[190:191], v[190:191], 0, s[74:75]
	v_lshl_add_u64 v[188:189], s[28:29], 0, v[188:189]
	v_lshl_add_u64 v[188:189], v[188:189], 0, s[74:75]
	s_mov_b32 m0, s72
	s_nop 0
	s_waitcnt lgkmcnt(8)
	s_barrier
	s_waitcnt lgkmcnt(0)
	s_setprio 1
	s_waitcnt lgkmcnt(0)
	v_mfma_f32_16x16x32_bf16 v[124:127], v[140:143], v[156:159], v[124:127]
	v_mfma_f32_16x16x32_bf16 v[120:123], v[148:151], v[156:159], v[120:123]
	v_mfma_f32_16x16x32_bf16 v[116:119], v[140:143], v[164:167], v[116:119]
	v_mfma_f32_16x16x32_bf16 v[112:115], v[148:151], v[164:167], v[112:115]
	v_mfma_f32_16x16x32_bf16 v[108:111], v[140:143], v[172:175], v[108:111]
	v_mfma_f32_16x16x32_bf16 v[104:107], v[148:151], v[172:175], v[104:107]
	v_mfma_f32_16x16x32_bf16 v[100:103], v[140:143], v[180:183], v[100:103]
	v_mfma_f32_16x16x32_bf16 v[96:99], v[148:151], v[180:183], v[96:99]
	v_mfma_f32_16x16x32_bf16 v[124:127], v[144:147], v[160:163], v[124:127]
	v_mfma_f32_16x16x32_bf16 v[120:123], v[152:155], v[160:163], v[120:123]
	v_mfma_f32_16x16x32_bf16 v[116:119], v[144:147], v[168:171], v[116:119]
	v_mfma_f32_16x16x32_bf16 v[112:115], v[152:155], v[168:171], v[112:115]
	v_mfma_f32_16x16x32_bf16 v[108:111], v[144:147], v[176:179], v[108:111]
	v_mfma_f32_16x16x32_bf16 v[104:107], v[152:155], v[176:179], v[104:107]
	v_mfma_f32_16x16x32_bf16 v[100:103], v[144:147], v[184:187], v[100:103]
	v_mfma_f32_16x16x32_bf16 v[96:99], v[152:155], v[184:187], v[96:99]
	s_setprio 0
	s_barrier
	v_mov_b32_e32 v196, v128
	v_mov_b32_e32 v210, v130
	ds_read_b128 v[188:191], v137
	ds_read_b128 v[192:195], v137 offset:1024
	ds_read_b128 v[202:205], v137 offset:2048
	ds_read_b128 v[206:209], v137 offset:3072
	v_mov_b32_e32 v211, v197
	v_lshl_add_u64 v[212:213], s[62:63], 0, v[196:197]
	s_mov_b32 m0, s66
	v_lshl_add_u64 v[212:213], v[212:213], 0, s[90:91]
	v_lshl_add_u64 v[210:211], s[62:63], 0, v[210:211]
	global_load_lds_dwordx4 v[212:213], off
	v_lshl_add_u64 v[210:211], v[210:211], 0, s[90:91]
	s_mov_b32 m0, s64
	s_nop 0
	global_load_lds_dwordx4 v[210:211], off
	s_barrier
	s_waitcnt lgkmcnt(0)
	s_setprio 1
	s_waitcnt lgkmcnt(0)
	v_mfma_f32_16x16x32_bf16 v[92:95], v[188:191], v[156:159], v[92:95]
	v_mfma_f32_16x16x32_bf16 v[88:91], v[202:205], v[156:159], v[88:91]
	v_mfma_f32_16x16x32_bf16 v[84:87], v[188:191], v[164:167], v[84:87]
	v_mfma_f32_16x16x32_bf16 v[80:83], v[202:205], v[164:167], v[80:83]
	v_mfma_f32_16x16x32_bf16 v[76:79], v[188:191], v[172:175], v[76:79]
	v_mfma_f32_16x16x32_bf16 v[72:75], v[202:205], v[172:175], v[72:75]
	v_mfma_f32_16x16x32_bf16 v[68:71], v[188:191], v[180:183], v[68:71]
	v_mfma_f32_16x16x32_bf16 v[64:67], v[202:205], v[180:183], v[64:67]
	v_mfma_f32_16x16x32_bf16 v[92:95], v[192:195], v[160:163], v[92:95]
	v_mfma_f32_16x16x32_bf16 v[88:91], v[206:209], v[160:163], v[88:91]
	v_mfma_f32_16x16x32_bf16 v[84:87], v[192:195], v[168:171], v[84:87]
	v_mfma_f32_16x16x32_bf16 v[80:83], v[206:209], v[168:171], v[80:83]
	v_mfma_f32_16x16x32_bf16 v[76:79], v[192:195], v[176:179], v[76:79]
	v_mfma_f32_16x16x32_bf16 v[72:75], v[206:209], v[176:179], v[72:75]
	v_mfma_f32_16x16x32_bf16 v[68:71], v[192:195], v[184:187], v[68:71]
	v_mfma_f32_16x16x32_bf16 v[64:67], v[206:209], v[184:187], v[64:67]
	s_setprio 0
	v_mov_b32_e32 v196, v128
	v_mov_b32_e32 v210, v130
	s_barrier
	v_mov_b32_e32 v211, v197
	v_lshl_add_u64 v[212:213], s[28:29], 0, v[196:197]
	s_mov_b32 m0, s65
	v_lshl_add_u64 v[212:213], v[212:213], 0, s[92:93]
	v_lshl_add_u64 v[210:211], s[28:29], 0, v[210:211]
	global_load_lds_dwordx4 v[212:213], off
	v_lshl_add_u64 v[210:211], v[210:211], 0, s[92:93]
	s_mov_b32 m0, s67
	s_nop 0
	global_load_lds_dwordx4 v[210:211], off
	s_waitcnt vmcnt(4)
	s_barrier
	v_mov_b32_e32 v196, v128
	v_mov_b32_e32 v140, v130
	v_mov_b32_e32 v141, v197
	v_lshl_add_u64 v[142:143], s[62:63], 0, v[196:197]
	s_mov_b32 m0, s33
	v_lshl_add_u64 v[142:143], v[142:143], 0, s[96:97]
	v_lshl_add_u64 v[140:141], s[62:63], 0, v[140:141]
	global_load_lds_dwordx4 v[142:143], off
	v_lshl_add_u64 v[140:141], v[140:141], 0, s[96:97]
	s_mov_b32 m0, s73
	s_nop 0
	global_load_lds_dwordx4 v[140:141], off
	s_barrier
	s_add_i32 s38, s38, 2
	s_add_u32 s60, s60, 0x100
	s_addc_u32 s61, s61, 0
	s_cmp_lt_u32 s38, 28
	s_cbranch_scc1 .Lh1_loop
	ds_read_b128 v[140:143], v129
	ds_read_b128 v[144:147], v129 offset:1024
	ds_read_b128 v[148:151], v129 offset:2048
	ds_read_b128 v[152:155], v129 offset:3072
	ds_read_b128 v[156:159], v136
	ds_read_b128 v[160:163], v136 offset:1024
	ds_read_b128 v[164:167], v135
	ds_read_b128 v[168:171], v135 offset:1024
	ds_read_b128 v[172:175], v134
	ds_read_b128 v[176:179], v134 offset:1024
	ds_read_b128 v[180:183], v133
	ds_read_b128 v[184:187], v133 offset:1024
	v_mov_b32_e32 v129, v197
	v_lshl_add_u64 v[128:129], s[58:59], 0, v[128:129]
	s_mov_b64 s[28:29], 0xf80
	s_mov_b32 m0, s40
	v_lshl_add_u64 v[128:129], v[128:129], 0, s[28:29]
	v_mov_b32_e32 v131, v197
	v_lshl_add_u64 v[128:129], s[58:59], 0, v[130:131]
	v_lshl_add_u64 v[128:129], v[128:129], 0, s[28:29]
	s_mov_b32 m0, s39
	s_nop 0
	s_barrier
	s_waitcnt lgkmcnt(0)
	s_setprio 1
	s_waitcnt lgkmcnt(0)
	v_mfma_f32_16x16x32_bf16 v[124:127], v[140:143], v[156:159], v[124:127]
	v_mfma_f32_16x16x32_bf16 v[120:123], v[148:151], v[156:159], v[120:123]
	v_mfma_f32_16x16x32_bf16 v[116:119], v[140:143], v[164:167], v[116:119]
	v_mfma_f32_16x16x32_bf16 v[112:115], v[148:151], v[164:167], v[112:115]
	v_mfma_f32_16x16x32_bf16 v[108:111], v[140:143], v[172:175], v[108:111]
	v_mfma_f32_16x16x32_bf16 v[100:103], v[140:143], v[180:183], v[100:103]
	v_mfma_f32_16x16x32_bf16 v[96:99], v[148:151], v[180:183], v[96:99]
	v_mfma_f32_16x16x32_bf16 v[124:127], v[144:147], v[160:163], v[124:127]
	v_mfma_f32_16x16x32_bf16 v[120:123], v[152:155], v[160:163], v[120:123]
	v_mfma_f32_16x16x32_bf16 v[116:119], v[144:147], v[168:171], v[116:119]
	v_mfma_f32_16x16x32_bf16 v[112:115], v[152:155], v[168:171], v[112:115]
	v_mfma_f32_16x16x32_bf16 v[108:111], v[144:147], v[176:179], v[108:111]
	v_mfma_f32_16x16x32_bf16 v[104:107], v[148:151], v[172:175], v[104:107]
	v_mfma_f32_16x16x32_bf16 v[100:103], v[144:147], v[184:187], v[100:103]
	v_mfma_f32_16x16x32_bf16 v[96:99], v[152:155], v[184:187], v[96:99]
	v_mfma_f32_16x16x32_bf16 v[128:131], v[152:155], v[176:179], v[104:107]
	s_setprio 0
	s_barrier
	s_nop 2
	ds_read_b128 v[104:107], v139
	ds_read_b128 v[188:191], v139 offset:1024
	ds_read_b128 v[192:195], v139 offset:2048
	ds_read_b128 v[202:205], v139 offset:3072
	s_barrier
	s_waitcnt lgkmcnt(0)
	s_setprio 1
	s_waitcnt lgkmcnt(0)
	v_mfma_f32_16x16x32_bf16 v[92:95], v[104:107], v[156:159], v[92:95]
	v_mfma_f32_16x16x32_bf16 v[84:87], v[104:107], v[164:167], v[84:87]
	v_mfma_f32_16x16x32_bf16 v[76:79], v[104:107], v[172:175], v[76:79]
	v_mfma_f32_16x16x32_bf16 v[68:71], v[104:107], v[180:183], v[68:71]
	v_mfma_f32_16x16x32_bf16 v[64:67], v[192:195], v[180:183], v[64:67]
	v_mfma_f32_16x16x32_bf16 v[92:95], v[188:191], v[160:163], v[92:95]
	v_mfma_f32_16x16x32_bf16 v[88:91], v[192:195], v[156:159], v[88:91]
	v_mfma_f32_16x16x32_bf16 v[84:87], v[188:191], v[168:171], v[84:87]
	v_mfma_f32_16x16x32_bf16 v[80:83], v[192:195], v[164:167], v[80:83]
	v_mfma_f32_16x16x32_bf16 v[76:79], v[188:191], v[176:179], v[76:79]
	v_mfma_f32_16x16x32_bf16 v[72:75], v[192:195], v[172:175], v[72:75]
	v_mfma_f32_16x16x32_bf16 v[68:71], v[188:191], v[184:187], v[68:71]
	v_mfma_f32_16x16x32_bf16 v[64:67], v[202:205], v[184:187], v[64:67]
	v_mfma_f32_16x16x32_bf16 v[156:159], v[202:205], v[160:163], v[88:91]
	v_mfma_f32_16x16x32_bf16 v[160:163], v[202:205], v[168:171], v[80:83]
	v_mfma_f32_16x16x32_bf16 v[164:167], v[202:205], v[176:179], v[72:75]
	s_setprio 0
	s_barrier
	s_nop 0
	s_waitcnt vmcnt(2)
	s_barrier
	s_waitcnt lgkmcnt(0)
	s_setprio 1
	s_waitcnt lgkmcnt(0)
	s_setprio 0
	s_setprio 1
	s_setprio 0
	s_barrier
	ds_read_b128 v[16:19], v138
	ds_read_b128 v[180:183], v138 offset:1024
	ds_read_b128 v[184:187], v138 offset:2048
	ds_read_b128 v[188:191], v138 offset:3072
	ds_read_b128 v[0:3], v136 offset:32768
	ds_read_b128 v[4:7], v136 offset:33792
	ds_read_b128 v[8:11], v135 offset:32768
	ds_read_b128 v[12:15], v135 offset:33792
	ds_read_b128 v[44:47], v134 offset:32768
	ds_read_b128 v[192:195], v134 offset:33792
	ds_read_b128 v[202:205], v133 offset:32768
	ds_read_b128 v[218:221], v133 offset:33792
	s_waitcnt vmcnt(0)
	s_barrier
	s_waitcnt lgkmcnt(0)
	s_setprio 1
	s_waitcnt lgkmcnt(0)
	v_mfma_f32_16x16x32_bf16 v[28:31], v[16:19], v[0:3], v[124:127]
	v_mfma_f32_16x16x32_bf16 v[52:55], v[180:183], v[4:7], v[28:31]
	v_mfma_f32_16x16x32_bf16 v[28:31], v[184:187], v[0:3], v[120:123]
	v_mfma_f32_16x16x32_bf16 v[104:107], v[188:191], v[4:7], v[28:31]
	v_mfma_f32_16x16x32_bf16 v[28:31], v[16:19], v[8:11], v[116:119]
	v_mfma_f32_16x16x32_bf16 v[72:75], v[180:183], v[12:15], v[28:31]
	v_mfma_f32_16x16x32_bf16 v[28:31], v[184:187], v[8:11], v[112:115]
	v_mfma_f32_16x16x32_bf16 v[116:119], v[188:191], v[12:15], v[28:31]
	v_mfma_f32_16x16x32_bf16 v[28:31], v[16:19], v[44:47], v[108:111]
	v_mfma_f32_16x16x32_bf16 v[80:83], v[180:183], v[192:195], v[28:31]
	v_mfma_f32_16x16x32_bf16 v[28:31], v[184:187], v[44:47], v[128:131]
	v_mfma_f32_16x16x32_bf16 v[108:111], v[188:191], v[192:195], v[28:31]
	v_mfma_f32_16x16x32_bf16 v[28:31], v[16:19], v[202:205], v[100:103]
	v_mfma_f32_16x16x32_bf16 v[88:91], v[180:183], v[218:221], v[28:31]
	v_mfma_f32_16x16x32_bf16 v[28:31], v[184:187], v[202:205], v[96:99]
	v_mfma_f32_16x16x32_bf16 v[96:99], v[188:191], v[218:221], v[28:31]
	s_setprio 0
	s_barrier
	ds_read_b128 v[128:131], v137
	ds_read_b128 v[222:225], v137 offset:1024
	ds_read_b128 v[228:231], v137 offset:2048
	ds_read_b128 v[232:235], v137 offset:3072
	s_waitcnt vmcnt(0)
	s_barrier
	s_waitcnt lgkmcnt(0)
	s_setprio 1
	s_waitcnt lgkmcnt(0)
	v_mfma_f32_16x16x32_bf16 v[28:31], v[128:131], v[0:3], v[92:95]
	v_mfma_f32_16x16x32_bf16 v[0:3], v[228:231], v[0:3], v[156:159]
	v_mfma_f32_16x16x32_bf16 v[28:31], v[222:225], v[4:7], v[28:31]
	v_mfma_f32_16x16x32_bf16 v[0:3], v[232:235], v[4:7], v[0:3]
	v_mfma_f32_16x16x32_bf16 v[4:7], v[128:131], v[8:11], v[84:87]
	v_mfma_f32_16x16x32_bf16 v[36:39], v[222:225], v[12:15], v[4:7]
	v_mfma_f32_16x16x32_bf16 v[4:7], v[228:231], v[8:11], v[160:163]
	v_mfma_f32_16x16x32_bf16 v[4:7], v[232:235], v[12:15], v[4:7]
	v_mfma_f32_16x16x32_bf16 v[8:11], v[128:131], v[44:47], v[76:79]
	v_mfma_f32_16x16x32_bf16 v[12:15], v[128:131], v[202:205], v[68:71]
	v_mfma_f32_16x16x32_bf16 v[40:43], v[222:225], v[192:195], v[8:11]
	v_mfma_f32_16x16x32_bf16 v[8:11], v[228:231], v[44:47], v[164:167]
	v_mfma_f32_16x16x32_bf16 v[44:47], v[222:225], v[218:221], v[12:15]
	v_mfma_f32_16x16x32_bf16 v[12:15], v[228:231], v[202:205], v[64:67]
	v_mfma_f32_16x16x32_bf16 v[8:11], v[232:235], v[192:195], v[8:11]
	v_mfma_f32_16x16x32_bf16 v[12:15], v[232:235], v[218:221], v[12:15]
	s_setprio 0
	s_barrier
	s_barrier
	s_waitcnt lgkmcnt(0)
	s_setprio 1
	s_waitcnt lgkmcnt(0)
	s_setprio 0
	s_setprio 1
	s_setprio 0
	s_movk_i32 s9, 0x100
	v_cmp_gt_u32_e32 vcc, s9, v132
	s_barrier
	s_and_saveexec_b64 s[28:29], vcc
	s_cbranch_execz .Lh1_epi
	s_barrier
